# attention: base-2 softmax only (log2e folded into scale, bias table and sink logit; 33 v_mul per key tile removed) on top of the padded-bias-table score path
# baseline (speedup 1.0000x reference)
; __device__ __forceinline__ void attn_item(const Params& P, const int pass, const int item, const int wvi) {
;     ...
;   if (tid < 257) fb[tid] = lptr(P.rel_bias)[(int)P.bucket[tid] * 16 + h];
.LBB0_555:
	v_mbcnt_lo_u32_b32 v100, -1, 0
	v_mbcnt_hi_u32_b32 v100, -1, v100
	s_and_b32 s2, s12, 15
	s_waitcnt vmcnt(5)
	v_add_u32_e32 v40, s48, v100
	v_cmp_gt_i32_e32 vcc, s97, v40
	s_and_saveexec_b64 s[0:1], vcc
	s_cbranch_execz .LBB0_557
	v_ashrrev_i32_e32 v41, 31, v40
	s_lshl_b32 s3, s2, 2
	v_lshl_add_u32 v1, v40, 2, 32
	v_add_u32_e32 v1, 0x241fc, v1
	v_readlane_b32 s4, v244, 52
	v_readlane_b32 s5, v244, 53
	v_readlane_b32 s6, v244, 54
	v_readlane_b32 s7, v244, 55
	v_lshl_or_b32 v0, v255, 6, s3
	v_add_u32_e32 v0, 0x23820, v0
	ds_read_b32 v0, v0
	s_waitcnt lgkmcnt(0)
	v_mul_f32_e32 v0, 0x3fb8aa3b, v0
	ds_write_b32 v1, v0

; #define ATT_ISSUE(kt_) do { const int ktn_ = (kt_); ATT_LD(0, pk0, pv0); ATT_LD(1, pk1, pv1); ATT_LD(2, pk2_, pv2); ATT_LD(3, pk3, pv3); } while (0)
; __device__ __forceinline__ void attn_item(const Params& P, const int pass, const int item, const int wvi) {
;   unsigned char* ws = wsp_plain(P);
;   const int tid = tidx(wvi), lane = tid & 63, w = wvi, fr = lane & 15, fq = lane >> 4;
;   const int S = (pass == 0) ? 2048 : 16384, nbs = S >> 7;
;   const int h = item & 15, blk = item >> 4, kvh = h >> 2;
;   const int nb = blk % nbs, seqbase = (blk / nbs) * S;
;   const int qb = blk * 128;
;   constexpr int LDV = 144;
;   constexpr int ATT_SET = 128 * LDP * 2 + 128 * LDV * 2;
;   float* fb = (float*)(smem + 2 * ATT_SET);
;   u16* qbuf = (u16*)(ws + OFF_Q);
;   const u16* kbuf = (const u16*)(ws + OFF_K);
;   const u16* vbuf = (const u16*)(ws + OFF_V);
;   if (tid < 257) fb[tid] = lptr(P.rel_bias)[(int)P.bucket[tid] * 16 + h];
;   bf16x8 qf[4];
; #pragma unroll
;   for (int kk = 0; kk < 4; ++kk) qf[kk] = *(const bf16x8*)(qbuf + (size_t)(qb + w * 16 + fr) * DM + h * 128 + kk * 32 + fq * 8);
;   float mrun = lptr(P.attn_sink)[h], lrun = 1.f;
;   f32x4 oacc[8];
; #pragma unroll
;   for (int i = 0; i < 8; ++i) oacc[i] = f32x4{0.f, 0.f, 0.f, 0.f};
;   const float scale = 0.08838834764831845f;
;   const int qi = w * 16 + fr;
;   const int kt_lo = (nb == 0) ? 1 : 0, kt_hi = (nb == nbs - 1) ? 1 : 2;
;   uint4 pk0, pk1, pk2_, pk3, pv0, pv1, pv2, pv3;
;     ...
;   if (w >= 4) __builtin_amdgcn_s_setprio(1);
;   ATT_ISSUE(kt_lo);
.LBB0_559:
	s_ashr_i32 s0, s0, 4
	s_abs_i32 s3, s0
	v_readlane_b32 s4, v243, 59
	s_mul_hi_u32 s4, s3, s4
	s_mul_i32 s5, s4, s34
	s_sub_i32 s3, s3, s5
	s_ashr_i32 s1, s0, 31
	s_add_i32 s5, s4, 1
	s_sub_i32 s6, s3, s34
	s_cmp_ge_u32 s3, s34
	s_cselect_b32 s4, s5, s4
	s_cselect_b32 s3, s6, s3
	s_add_i32 s5, s4, 1
	s_cmp_ge_u32 s3, s34
	s_cselect_b32 s3, s5, s4
	s_xor_b32 s3, s3, s1
	s_sub_i32 s3, s3, s1
	s_mul_i32 s1, s3, s34
	s_sub_i32 s8, s0, s1
	s_cmp_eq_u32 s8, 0
	v_readlane_b32 s4, v243, 41
	s_cselect_b64 s[0:1], -1, 0
	s_cmp_eq_u32 s8, s4
	v_readlane_b32 s5, v243, 56
	s_cselect_b32 s4, 1, 2
	s_lshl_b32 s5, s3, s5
	s_ashr_i32 s6, s5, 31
	s_add_i32 s7, s8, -1
	s_cmp_lg_u64 s[0:1], 0
	v_cndmask_b32_e64 v49, 0, 1, s[0:1]
	s_addc_u32 s0, s8, -1
	s_ashr_i32 s1, s0, 31
	v_ashrrev_i32_e32 v86, 4, v40
	s_lshl_b64 s[0:1], s[0:1], 7
	v_add_u32_e32 v24, 0x200, v40
	v_add_u32_e32 v32, 0x400, v40
	v_add_u32_e32 v40, 0x600, v40
	s_add_u32 s0, s0, s5
	v_ashrrev_i32_e32 v90, 4, v24
	v_ashrrev_i32_e32 v92, 4, v32
	v_ashrrev_i32_e32 v94, 4, v40
	s_addc_u32 s1, s1, s6
	v_ashrrev_i32_e32 v87, 31, v86
	s_lshl_b32 s2, s2, 6
	v_ashrrev_i32_e32 v91, 31, v90
	v_ashrrev_i32_e32 v93, 31, v92
	v_ashrrev_i32_e32 v95, 31, v94
	v_lshl_add_u64 v[16:17], s[0:1], 0, v[86:87]
	v_readlane_b32 s10, v245, 21
	s_and_b32 s18, s2, 0x300
	v_readlane_b32 s2, v245, 23
	v_lshl_add_u64 v[24:25], s[0:1], 0, v[90:91]
	v_lshl_add_u64 v[32:33], s[0:1], 0, v[92:93]
	v_lshl_add_u64 v[40:41], s[0:1], 0, v[94:95]
	v_lshlrev_b64 v[16:17], 10, v[16:17]
	v_readlane_b32 s11, v245, 22
	v_lshlrev_b32_e32 v20, 3, v100
	v_readlane_b32 s3, v245, 24
	v_lshlrev_b64 v[24:25], 10, v[24:25]
	v_lshlrev_b64 v[32:33], 10, v[32:33]
	v_lshlrev_b64 v[40:41], 10, v[40:41]
	v_lshl_add_u64 v[18:19], s[10:11], 0, v[16:17]
	v_and_b32_e32 v20, 0x78, v20
	v_lshl_add_u64 v[16:17], s[2:3], 0, v[16:17]
	v_lshl_add_u64 v[26:27], s[10:11], 0, v[24:25]
	v_lshl_add_u64 v[24:25], s[2:3], 0, v[24:25]
	v_lshl_add_u64 v[34:35], s[10:11], 0, v[32:33]
	v_lshl_add_u64 v[32:33], s[2:3], 0, v[32:33]
	v_lshl_add_u64 v[42:43], s[10:11], 0, v[40:41]
	v_lshl_add_u64 v[40:41], s[2:3], 0, v[40:41]
	v_lshl_add_u64 v[18:19], v[18:19], 0, s[18:19]
	v_lshlrev_b32_e32 v88, 1, v20
	v_mov_b32_e32 v89, v145
	v_lshl_add_u64 v[16:17], v[16:17], 0, s[18:19]
	v_lshl_add_u64 v[26:27], v[26:27], 0, s[18:19]
	v_lshl_add_u64 v[24:25], v[24:25], 0, s[18:19]
	v_lshl_add_u64 v[34:35], v[34:35], 0, s[18:19]
	v_lshl_add_u64 v[32:33], v[32:33], 0, s[18:19]
	v_lshl_add_u64 v[42:43], v[42:43], 0, s[18:19]
	v_lshl_add_u64 v[40:41], v[40:41], 0, s[18:19]
	v_lshl_add_u64 v[18:19], v[18:19], 0, v[88:89]
	v_lshl_add_u64 v[20:21], v[16:17], 0, v[88:89]
	v_lshl_add_u64 v[26:27], v[26:27], 0, v[88:89]
	v_lshl_add_u64 v[28:29], v[24:25], 0, v[88:89]
	v_lshl_add_u64 v[34:35], v[34:35], 0, v[88:89]
	v_lshl_add_u64 v[36:37], v[32:33], 0, v[88:89]
	v_lshl_add_u64 v[42:43], v[42:43], 0, v[88:89]
	s_waitcnt vmcnt(9)
	v_lshl_add_u64 v[44:45], v[40:41], 0, v[88:89]
	global_load_dwordx4 v[16:19], v[18:19], off
	s_nop 0
	global_load_dwordx4 v[20:23], v[20:21], off
	s_nop 0
	global_load_dwordx4 v[24:27], v[26:27], off
	s_nop 0
	global_load_dwordx4 v[28:31], v[28:29], off
	s_nop 0
	global_load_dwordx4 v[32:35], v[34:35], off
	s_nop 0
	global_load_dwordx4 v[36:39], v[36:37], off
	s_nop 0
	global_load_dwordx4 v[40:43], v[42:43], off
	s_nop 0
	global_load_dwordx4 v[44:47], v[44:45], off
	s_movk_i32 s0, 0x120
	s_movk_i32 s1, 0x110
	v_mul_lo_u32 v102, v86, s0
	v_mul_lo_u32 v104, v90, s0
	v_mul_lo_u32 v106, v92, s0
	v_mul_lo_u32 v108, v94, s0
	s_add_u32 s0, s10, s18
	v_mul_lo_u32 v101, v86, s1
	v_mul_lo_u32 v103, v90, s1
	v_mul_lo_u32 v105, v92, s1
	v_mul_lo_u32 v107, v94, s1
	s_addc_u32 s1, s11, 0
	v_and_b32_e32 v50, 63, v100
	v_lshl_add_u64 v[96:97], s[0:1], 0, v[88:89]
	s_add_u32 s0, s2, s18
	v_bfe_u32 v51, v100, 4, 2
	s_addc_u32 s1, s3, 0
	v_lshlrev_b32_e32 v50, 2, v50
	v_lshl_add_u64 v[98:99], s[0:1], 0, v[88:89]
	v_lshlrev_b32_e32 v89, 2, v51
	v_xor_b32_e32 v109, 64, v50
	v_xor_b32_e32 v110, 0x80, v50
	v_lshrrev_b32_e32 v50, 2, v48
	v_or_b32_e32 v50, v89, v50
	v_mul_u32_u24_e32 v112, 0x120, v50
	v_lshlrev_b32_e32 v50, 7, v49
	v_readlane_b32 s0, v244, 29
	v_readfirstlane_b32 s8, v49
	v_mul_u32_u24_e32 v111, 0x110, v48
	v_add_u32_e32 v50, s0, v50
	v_add_u32_e32 v50, v50, v89
	v_sub_u32_e32 v113, v50, v48
	v_lshlrev_b32_e32 v50, 4, v51
	v_lshl_or_b32 v49, v49, 9, v50
	v_lshlrev_b32_e32 v48, 2, v48
	s_waitcnt vmcnt(16)
	v_lshlrev_b32_e32 v52, 2, v100
	v_sub_u32_e32 v48, v49, v48
	v_readlane_b32 s0, v244, 27
	v_and_b32_e32 v52, 12, v52
	v_mov_b32_e32 v116, 1.0
	v_add_u32_e32 v114, s0, v48
	v_add_u32_e32 v114, 0x11fc, v114
	v_mov_b32_e32 v48, 0
	v_lshlrev_b32_e32 v115, 1, v52
	v_mov_b32_e32 v49, v48
	v_mov_b32_e32 v50, v48
	v_mov_b32_e32 v51, v48
	v_mov_b32_e32 v56, v48
	v_mov_b32_e32 v57, v48
	v_mov_b32_e32 v58, v48
	v_mov_b32_e32 v59, v48
	v_mov_b32_e32 v52, v48
	v_mov_b32_e32 v53, v48
	v_mov_b32_e32 v54, v48
	v_mov_b32_e32 v55, v48
	v_mov_b32_e32 v60, v48
	v_mov_b32_e32 v61, v48
	v_mov_b32_e32 v62, v48
	v_mov_b32_e32 v63, v48
	v_mov_b32_e32 v64, v48
	v_mov_b32_e32 v65, v48
	v_mov_b32_e32 v66, v48
	v_mov_b32_e32 v67, v48
	v_mov_b32_e32 v68, v48
	v_mov_b32_e32 v69, v48
	v_mov_b32_e32 v70, v48
	v_mov_b32_e32 v71, v48
	v_mov_b32_e32 v72, v48
	v_mov_b32_e32 v73, v48
	v_mov_b32_e32 v74, v48
	v_mov_b32_e32 v75, v48
	v_mov_b32_e32 v76, v48
	v_mov_b32_e32 v77, v48
	v_mov_b32_e32 v78, v48
	v_mov_b32_e32 v79, v48
	s_waitcnt vmcnt(0)
	v_mul_f32_e32 v117, 0x3fb8aa3b, v117
; #define ATT_ISSUE(kt_) do { const int ktn_ = (kt_); ATT_LD(0, pk0, pv0); ATT_LD(1, pk1, pv1); ATT_LD(2, pk2_, pv2); ATT_LD(3, pk3, pv3); } while (0)
; #define ATT_ST(i, RK, RV) do { const int q = tid + NTHR * (i), row = q >> 4, c16 = q & 15; \
;       *(uint4*)(Ks + row * LDP + c16 * 8) = RK; *(uint4*)(Vs + row * LDV + c16 * 8) = RV; } while (0)
; __device__ __forceinline__ void attn_item(const Params& P, const int pass, const int item, const int wvi) {
;     ...
;   for (int kt = kt_lo; kt <= kt_hi; ++kt) {
;     u16* Ks = (u16*)(smem + (kt & 1) * ATT_SET);
;     u16* Vs = Ks + 128 * LDP;
;     ATT_ST(0, pk0, pv0); ATT_ST(1, pk1, pv1); ATT_ST(2, pk2_, pv2); ATT_ST(3, pk3, pv3);
;     __syncthreads();
;     ATT_ISSUE((kt < kt_hi) ? kt + 1 : kt);
;     f32x4 sc[8];
;     float mx = -INFINITY;
; #pragma unroll
;     for (int t8 = 0; t8 < 8; ++t8) {
;       f32x4 a = f32x4{0.f, 0.f, 0.f, 0.f};
; #pragma unroll
;       for (int kk = 0; kk < 4; ++kk) {
;         bf16x8 kf = *(const bf16x8*)(Ks + (t8 * 16 + fr) * LDP + kk * 32 + fq * 8);
;         a = __builtin_amdgcn_mfma_f32_16x16x32_bf16(kf, qf[kk], a, 0, 0, 0);
;       }
; #pragma unroll
;       for (int j = 0; j < 4; ++j) {
;         const int rel = (kt - 1) * 128 + t8 * 16 + fq * 4 + j - qi;
;         const bool ok = (rel >= -128) && (rel <= 128);
;         const int ri = ok ? rel + 128 : 0;
;         const float v = ok ? (a[j] * scale + fb[ri]) : -INFINITY;
;         a[j] = v;
;         mx = fmaxf(mx, v);
;       }
;       sc[t8] = a;
.LBB0_560:
	s_bitcmp1_b32 s8, 0
	s_cselect_b32 s0, 0x11800, 0
	s_add_i32 s9, s0, 32
	s_cmp_ge_u32 s8, s4
	s_mov_b32 s2, s8
	v_add3_u32 v80, s9, v101, v88
	s_cselect_b64 s[0:1], -1, 0
	s_add_i32 s8, s8, 1
	s_waitcnt vmcnt(7)
	ds_write_b128 v80, v[16:19]
	v_add3_u32 v16, s9, v102, v88
	s_cmp_lt_u32 s2, s4
	s_waitcnt vmcnt(6)
	ds_write_b128 v16, v[20:23] offset:34816
	v_add3_u32 v16, s9, v103, v88
	s_cselect_b32 s2, s8, s2
	s_waitcnt vmcnt(5)
	ds_write_b128 v16, v[24:27]
	v_add3_u32 v16, s9, v104, v88
	s_add_i32 s2, s2, s7
	s_waitcnt vmcnt(4)
	ds_write_b128 v16, v[28:31] offset:34816
	v_add3_u32 v16, s9, v105, v88
	s_ashr_i32 s3, s2, 31
	s_waitcnt vmcnt(3)
	ds_write_b128 v16, v[32:35]
	v_add3_u32 v16, s9, v106, v88
	s_lshl_b64 s[2:3], s[2:3], 7
	s_waitcnt vmcnt(2)
	ds_write_b128 v16, v[36:39] offset:34816
	v_add3_u32 v16, s9, v107, v88
	s_add_u32 s2, s2, s5
	s_waitcnt vmcnt(1)
	ds_write_b128 v16, v[40:43]
	v_add3_u32 v16, s9, v108, v88
	s_addc_u32 s3, s3, s6
	s_waitcnt vmcnt(0)
	ds_write_b128 v16, v[44:47] offset:34816
	v_lshl_add_u64 v[16:17], s[2:3], 0, v[86:87]
	v_lshlrev_b64 v[16:17], 10, v[16:17]
	v_add_u32_e32 v28, s9, v144
	v_lshl_add_u64 v[18:19], v[96:97], 0, v[16:17]
	v_lshl_add_u64 v[20:21], v[98:99], 0, v[16:17]
	v_add_u32_e32 v126, v28, v111
	s_waitcnt lgkmcnt(0)
	s_barrier
	ds_read_b32 v210, v114
	ds_read_b32 v211, v114 offset:4
	ds_read_b32 v212, v114 offset:8
	ds_read_b32 v213, v114 offset:12
	global_load_dwordx4 v[16:19], v[18:19], off
	s_nop 0
	global_load_dwordx4 v[20:23], v[20:21], off
	ds_read_b128 v[32:35], v126
	v_lshl_add_u64 v[24:25], s[2:3], 0, v[90:91]
	v_lshlrev_b64 v[24:25], 10, v[24:25]
	v_lshl_add_u64 v[26:27], v[96:97], 0, v[24:25]
	v_lshl_add_u64 v[28:29], v[98:99], 0, v[24:25]
	global_load_dwordx4 v[24:27], v[26:27], off
	s_nop 0
	global_load_dwordx4 v[28:31], v[28:29], off
	ds_read_b128 v[40:43], v126 offset:64
	ds_read_b128 v[80:83], v126 offset:128
	s_waitcnt lgkmcnt(2)
	v_mfma_f32_16x16x32_bf16 v[44:47], v[32:35], v[0:3], 0
	v_lshl_add_u64 v[36:37], s[2:3], 0, v[92:93]
	v_lshl_add_u64 v[118:119], s[2:3], 0, v[94:95]
	v_lshlrev_b64 v[36:37], 10, v[36:37]
	s_waitcnt lgkmcnt(1)
	v_mfma_f32_16x16x32_bf16 v[40:43], v[40:43], v[4:7], v[44:47]
	v_lshlrev_b64 v[118:119], 10, v[118:119]
	v_lshl_add_u64 v[38:39], v[96:97], 0, v[36:37]
	v_lshl_add_u64 v[36:37], v[98:99], 0, v[36:37]
	v_lshl_add_u64 v[44:45], v[96:97], 0, v[118:119]
	v_lshl_add_u64 v[46:47], v[98:99], 0, v[118:119]
	global_load_dwordx4 v[32:35], v[38:39], off
	s_nop 0
	global_load_dwordx4 v[36:39], v[36:37], off
	ds_read_b128 v[118:121], v126 offset:192
	s_waitcnt lgkmcnt(1)
	v_mfma_f32_16x16x32_bf16 v[80:83], v[80:83], v[8:11], v[40:43]
	s_nop 2
	global_load_dwordx4 v[40:43], v[44:45], off
	s_nop 0
	global_load_dwordx4 v[44:47], v[46:47], off
	v_cmp_gt_u32_e32 vcc, s97, v113
	s_waitcnt lgkmcnt(0)
	v_mfma_f32_16x16x32_bf16 v[80:83], v[118:121], v[12:15], v[80:83]
	ds_read_b32 v215, v114 offset:64
	ds_read_b32 v216, v114 offset:68
	ds_read_b32 v217, v114 offset:72
	ds_read_b32 v218, v114 offset:76
	s_nop 3
	v_fmamk_f32 v121, v80, 0x3e0293ee, v210
	v_fmamk_f32 v118, v81, 0x3e0293ee, v211
	v_fmamk_f32 v124, v82, 0x3e0293ee, v212
	v_fmamk_f32 v119, v83, 0x3e0293ee, v213
	ds_read_b128 v[80:83], v126 offset:4352
	ds_read_b128 v[176:179], v126 offset:4416
	ds_read_b128 v[180:183], v126 offset:4480
	ds_read_b128 v[190:193], v126 offset:4544
	s_waitcnt lgkmcnt(3)
	v_mfma_f32_16x16x32_bf16 v[80:83], v[80:83], v[0:3], 0
	s_waitcnt lgkmcnt(2)
	v_mfma_f32_16x16x32_bf16 v[80:83], v[176:179], v[4:7], v[80:83]
	s_waitcnt lgkmcnt(1)
	v_mfma_f32_16x16x32_bf16 v[80:83], v[180:183], v[8:11], v[80:83]
	s_waitcnt lgkmcnt(0)
	v_mfma_f32_16x16x32_bf16 v[80:83], v[190:193], v[12:15], v[80:83]
	ds_read_b32 v210, v114 offset:128
	ds_read_b32 v211, v114 offset:132
	ds_read_b32 v212, v114 offset:136
	ds_read_b32 v213, v114 offset:140
	s_nop 3
	v_fmamk_f32 v122, v80, 0x3e0293ee, v215
	v_fmamk_f32 v120, v81, 0x3e0293ee, v216
	v_fmamk_f32 v125, v82, 0x3e0293ee, v217
	v_fmamk_f32 v123, v83, 0x3e0293ee, v218
	ds_read_b128 v[80:83], v126 offset:8704
	ds_read_b128 v[176:179], v126 offset:8768
	ds_read_b128 v[180:183], v126 offset:8832
	ds_read_b128 v[190:193], v126 offset:8896
	s_waitcnt lgkmcnt(3)
	v_mfma_f32_16x16x32_bf16 v[80:83], v[80:83], v[0:3], 0
	s_waitcnt lgkmcnt(2)
	v_mfma_f32_16x16x32_bf16 v[80:83], v[176:179], v[4:7], v[80:83]
	s_waitcnt lgkmcnt(1)
	v_mfma_f32_16x16x32_bf16 v[80:83], v[180:183], v[8:11], v[80:83]
	s_waitcnt lgkmcnt(0)
	v_mfma_f32_16x16x32_bf16 v[80:83], v[190:193], v[12:15], v[80:83]
	ds_read_b32 v215, v114 offset:192
	ds_read_b32 v216, v114 offset:196
	ds_read_b32 v217, v114 offset:200
	ds_read_b32 v218, v114 offset:204
	s_nop 3
	v_fmamk_f32 v128, v80, 0x3e0293ee, v210
	v_fmamk_f32 v127, v81, 0x3e0293ee, v211
	v_fmamk_f32 v130, v82, 0x3e0293ee, v212
	v_fmamk_f32 v129, v83, 0x3e0293ee, v213
	ds_read_b128 v[80:83], v126 offset:13056
	ds_read_b128 v[176:179], v126 offset:13120
	ds_read_b128 v[180:183], v126 offset:13184
	ds_read_b128 v[190:193], v126 offset:13248
	s_waitcnt lgkmcnt(3)
	v_mfma_f32_16x16x32_bf16 v[80:83], v[80:83], v[0:3], 0
	s_waitcnt lgkmcnt(2)
	v_mfma_f32_16x16x32_bf16 v[80:83], v[176:179], v[4:7], v[80:83]
	s_waitcnt lgkmcnt(1)
	v_mfma_f32_16x16x32_bf16 v[80:83], v[180:183], v[8:11], v[80:83]
	s_waitcnt lgkmcnt(0)
	v_mfma_f32_16x16x32_bf16 v[80:83], v[190:193], v[12:15], v[80:83]
	ds_read_b32 v210, v114 offset:256
	ds_read_b32 v211, v114 offset:260
	ds_read_b32 v212, v114 offset:264
	ds_read_b32 v213, v114 offset:268
	s_nop 3
	v_fmamk_f32 v136, v80, 0x3e0293ee, v215
	v_fmamk_f32 v131, v81, 0x3e0293ee, v216
	v_fmamk_f32 v138, v82, 0x3e0293ee, v217
	v_fmamk_f32 v139, v83, 0x3e0293ee, v218
	ds_read_b128 v[80:83], v126 offset:17408
	ds_read_b128 v[176:179], v126 offset:17472
	ds_read_b128 v[180:183], v126 offset:17536
	ds_read_b128 v[190:193], v126 offset:17600
	s_waitcnt lgkmcnt(3)
; __device__ __forceinline__ void attn_item(const Params& P, const int pass, const int item, const int wvi) {
;     ...
;     for (int t8 = 0; t8 < 8; ++t8) {
;       f32x4 a = f32x4{0.f, 0.f, 0.f, 0.f};
; #pragma unroll
;       for (int kk = 0; kk < 4; ++kk) {
;         bf16x8 kf = *(const bf16x8*)(Ks + (t8 * 16 + fr) * LDP + kk * 32 + fq * 8);
;         a = __builtin_amdgcn_mfma_f32_16x16x32_bf16(kf, qf[kk], a, 0, 0, 0);
;       }
; #pragma unroll
;       for (int j = 0; j < 4; ++j) {
;         const int rel = (kt - 1) * 128 + t8 * 16 + fq * 4 + j - qi;
;         const bool ok = (rel >= -128) && (rel <= 128);
;         const int ri = ok ? rel + 128 : 0;
;         const float v = ok ? (a[j] * scale + fb[ri]) : -INFINITY;
;         a[j] = v;
;         mx = fmaxf(mx, v);
;       }
;       sc[t8] = a;
;     }
;     mx = fmaxf(mx, shfl_src(mx, lane ^ 16));
;     mx = fmaxf(mx, shfl_src(mx, lane ^ 32));
;     const float mnew = fmaxf(mrun, mx);
;     const float alpha = __expf(mrun - mnew);
;     float psum = 0.f;
; #pragma unroll
;     for (int t8 = 0; t8 < 8; ++t8)
; #pragma unroll
;       for (int j = 0; j < 4; ++j) { const float pv = __expf(sc[t8][j] - mnew); sc[t8][j] = pv; psum += pv; }
;     psum += shfl_src(psum, lane ^ 16);
;     psum += shfl_src(psum, lane ^ 32);
;     lrun = lrun * alpha + psum;
;     mrun = mnew;
	v_mfma_f32_16x16x32_bf16 v[80:83], v[80:83], v[0:3], 0
	s_waitcnt lgkmcnt(2)
	v_mfma_f32_16x16x32_bf16 v[80:83], v[176:179], v[4:7], v[80:83]
	s_waitcnt lgkmcnt(1)
	v_mfma_f32_16x16x32_bf16 v[80:83], v[180:183], v[8:11], v[80:83]
	s_waitcnt lgkmcnt(0)
	v_mfma_f32_16x16x32_bf16 v[80:83], v[190:193], v[12:15], v[80:83]
	ds_read_b32 v215, v114 offset:320
	ds_read_b32 v216, v114 offset:324
	ds_read_b32 v217, v114 offset:328
	ds_read_b32 v218, v114 offset:332
	s_nop 3
	v_fmamk_f32 v141, v80, 0x3e0293ee, v210
	v_fmamk_f32 v140, v81, 0x3e0293ee, v211
	v_fmamk_f32 v143, v82, 0x3e0293ee, v212
	v_fmamk_f32 v142, v83, 0x3e0293ee, v213
	ds_read_b128 v[80:83], v126 offset:21760
	ds_read_b128 v[176:179], v126 offset:21824
	ds_read_b128 v[180:183], v126 offset:21888
	ds_read_b128 v[190:193], v126 offset:21952
	s_waitcnt lgkmcnt(3)
	v_mfma_f32_16x16x32_bf16 v[80:83], v[80:83], v[0:3], 0
	s_waitcnt lgkmcnt(2)
	v_mfma_f32_16x16x32_bf16 v[80:83], v[176:179], v[4:7], v[80:83]
	s_waitcnt lgkmcnt(1)
	v_mfma_f32_16x16x32_bf16 v[80:83], v[180:183], v[8:11], v[80:83]
	s_waitcnt lgkmcnt(0)
	v_mfma_f32_16x16x32_bf16 v[80:83], v[190:193], v[12:15], v[80:83]
	ds_read_b32 v210, v114 offset:384
	ds_read_b32 v211, v114 offset:388
	ds_read_b32 v212, v114 offset:392
	ds_read_b32 v213, v114 offset:396
	s_nop 3
	v_fmamk_f32 v149, v80, 0x3e0293ee, v215
	v_fmamk_f32 v148, v81, 0x3e0293ee, v216
	v_fmamk_f32 v152, v82, 0x3e0293ee, v217
	v_fmamk_f32 v151, v83, 0x3e0293ee, v218
	ds_read_b128 v[80:83], v126 offset:26112
	ds_read_b128 v[176:179], v126 offset:26176
	ds_read_b128 v[180:183], v126 offset:26240
	ds_read_b128 v[190:193], v126 offset:26304
	s_waitcnt lgkmcnt(3)
	v_mfma_f32_16x16x32_bf16 v[80:83], v[80:83], v[0:3], 0
	s_waitcnt lgkmcnt(2)
	v_mfma_f32_16x16x32_bf16 v[80:83], v[176:179], v[4:7], v[80:83]
	s_waitcnt lgkmcnt(1)
	v_mfma_f32_16x16x32_bf16 v[80:83], v[180:183], v[8:11], v[80:83]
	s_waitcnt lgkmcnt(0)
	v_mfma_f32_16x16x32_bf16 v[80:83], v[190:193], v[12:15], v[80:83]
	ds_read_b32 v215, v114 offset:448
	ds_read_b32 v216, v114 offset:452
	ds_read_b32 v217, v114 offset:456
	ds_read_b32 v218, v114 offset:460
	s_nop 3
	v_fmamk_f32 v154, v80, 0x3e0293ee, v210
	v_fmamk_f32 v153, v81, 0x3e0293ee, v211
	v_fmamk_f32 v156, v82, 0x3e0293ee, v212
	v_fmamk_f32 v155, v83, 0x3e0293ee, v213
	ds_read_b128 v[80:83], v126 offset:30464
	ds_read_b128 v[176:179], v126 offset:30528
	ds_read_b128 v[180:183], v126 offset:30592
	ds_read_b128 v[190:193], v126 offset:30656
	s_waitcnt lgkmcnt(3)
	v_mfma_f32_16x16x32_bf16 v[80:83], v[80:83], v[0:3], 0
	s_waitcnt lgkmcnt(2)
	v_mfma_f32_16x16x32_bf16 v[80:83], v[176:179], v[4:7], v[80:83]
	s_waitcnt lgkmcnt(1)
	v_mfma_f32_16x16x32_bf16 v[80:83], v[180:183], v[8:11], v[80:83]
	s_waitcnt lgkmcnt(0)
	v_mfma_f32_16x16x32_bf16 v[80:83], v[190:193], v[12:15], v[80:83]
	s_nop 3
	s_nop 3
	v_fmamk_f32 v158, v80, 0x3e0293ee, v215
	v_fmamk_f32 v157, v81, 0x3e0293ee, v216
	v_fmamk_f32 v159, v82, 0x3e0293ee, v217
	v_fmamk_f32 v80, v83, 0x3e0293ee, v218
	s_mov_b32 s2, 0xff800000
	v_max3_f32 v81, v121, s2, v118
	v_max3_f32 v81, v81, v124, v119
	v_max3_f32 v81, v81, v122, v120
	v_max3_f32 v81, v81, v125, v123
	v_max3_f32 v81, v81, v128, v127
	v_max3_f32 v81, v81, v130, v129
	v_max3_f32 v81, v81, v136, v131
	v_max3_f32 v81, v81, v138, v139
	v_max3_f32 v81, v81, v141, v140
	v_max3_f32 v81, v81, v143, v142
	v_max3_f32 v81, v81, v149, v148
	v_max3_f32 v81, v81, v152, v151
	v_max3_f32 v81, v81, v154, v153
	v_max3_f32 v81, v81, v156, v155
	v_max3_f32 v81, v81, v158, v157
	v_max3_f32 v81, v81, v159, v80
	ds_bpermute_b32 v82, v109, v81
	v_add_u32_e32 v113, 0x80, v113
	v_add_u32_e32 v114, 0x200, v114
	s_andn2_b64 vcc, exec, s[0:1]
	s_waitcnt lgkmcnt(0)
	v_max_f32_e32 v82, v82, v82
	v_max_f32_e32 v81, v81, v82
	ds_bpermute_b32 v82, v110, v81
	s_waitcnt lgkmcnt(0)
	v_max3_f32 v81, v117, v81, v82
	v_sub_f32_e32 v82, v117, v81
	v_sub_f32_e32 v117, v118, v81
	v_exp_f32_e32 v147, v117
	v_sub_f32_e32 v117, v124, v81
	v_exp_f32_e32 v150, v117
	v_sub_f32_e32 v117, v119, v81
	v_exp_f32_e32 v164, v117
	v_sub_f32_e32 v117, v122, v81
	v_exp_f32_e32 v166, v117
	v_sub_f32_e32 v117, v120, v81
	v_exp_f32_e32 v172, v117
	v_sub_f32_e32 v117, v125, v81
	v_exp_f32_e32 v173, v117
	v_sub_f32_e32 v117, v123, v81
	v_exp_f32_e32 v174, v117
	v_sub_f32_e32 v117, v128, v81
	v_exp_f32_e32 v132, v117
	v_sub_f32_e32 v117, v127, v81
	v_exp_f32_e32 v133, v117
	v_sub_f32_e32 v117, v130, v81
	v_exp_f32_e32 v134, v117
	v_sub_f32_e32 v117, v129, v81
	v_sub_f32_e32 v83, v121, v81
	v_exp_f32_e32 v135, v117
	v_sub_f32_e32 v117, v136, v81
	v_exp_f32_e32 v146, v83
	v_exp_f32_e32 v136, v117
	v_sub_f32_e32 v117, v131, v81
	v_exp_f32_e32 v137, v117
	v_sub_f32_e32 v117, v138, v81
	v_add_f32_e32 v83, 0, v146
	v_add_f32_e32 v83, v147, v83
	v_exp_f32_e32 v138, v117
	v_sub_f32_e32 v117, v139, v81
	v_add_f32_e32 v83, v150, v83
	v_add_f32_e32 v83, v164, v83
	v_exp_f32_e32 v139, v117
	v_sub_f32_e32 v117, v141, v81
	v_add_f32_e32 v83, v166, v83
	v_add_f32_e32 v83, v172, v83
	v_exp_f32_e32 v124, v117
	v_sub_f32_e32 v117, v140, v81
	v_add_f32_e32 v83, v173, v83
	v_add_f32_e32 v83, v174, v83
	v_exp_f32_e32 v125, v117
	v_sub_f32_e32 v117, v143, v81
	v_add_f32_e32 v83, v132, v83
	v_add_f32_e32 v83, v133, v83
	v_exp_f32_e32 v126, v117
	v_sub_f32_e32 v117, v142, v81
	v_add_f32_e32 v83, v134, v83
	v_add_f32_e32 v83, v135, v83
	v_exp_f32_e32 v127, v117
	v_sub_f32_e32 v117, v149, v81
	v_add_f32_e32 v83, v136, v83
	v_add_f32_e32 v83, v137, v83
	v_exp_f32_e32 v128, v117
	v_sub_f32_e32 v117, v148, v81
	v_add_f32_e32 v83, v138, v83
	v_add_f32_e32 v83, v139, v83
	v_exp_f32_e32 v129, v117
	v_sub_f32_e32 v117, v152, v81
	v_add_f32_e32 v83, v124, v83
	v_add_f32_e32 v83, v125, v83
	v_exp_f32_e32 v130, v117
	v_sub_f32_e32 v117, v151, v81
	v_add_f32_e32 v83, v126, v83
	v_add_f32_e32 v83, v127, v83
	v_exp_f32_e32 v131, v117
	v_add_f32_e32 v83, v128, v83
	v_add_f32_e32 v83, v129, v83
	v_add_f32_e32 v83, v130, v83
	v_add_f32_e32 v117, v131, v83
	v_sub_f32_e32 v83, v154, v81
	v_exp_f32_e32 v83, v83
	v_sub_f32_e32 v80, v80, v81
	v_add_f32_e32 v118, v83, v117
	v_sub_f32_e32 v117, v153, v81
	v_exp_f32_e32 v117, v117
	s_nop 0
	v_add_f32_e32 v119, v117, v118
	v_sub_f32_e32 v118, v156, v81
	v_exp_f32_e32 v118, v118
	s_nop 0
	v_add_f32_e32 v120, v118, v119
	v_sub_f32_e32 v119, v155, v81
	v_exp_f32_e32 v119, v119
	s_nop 0
	v_add_f32_e32 v121, v119, v120
	v_sub_f32_e32 v120, v158, v81
	v_exp_f32_e32 v120, v120
	s_nop 0
	v_add_f32_e32 v122, v120, v121
	v_sub_f32_e32 v121, v157, v81
	v_exp_f32_e32 v121, v121
	s_nop 0
	v_add_f32_e32 v123, v121, v122
	v_sub_f32_e32 v122, v159, v81
	v_exp_f32_e32 v122, v122
	s_nop 0
	v_add_f32_e32 v140, v122, v123
	v_exp_f32_e32 v123, v80
	v_exp_f32_e32 v80, v82
	v_add_f32_e32 v140, v123, v140
	ds_bpermute_b32 v82, v109, v140
	v_pk_mul_f32 v[160:161], v[60:61], v[80:81] op_sel_hi:[1,0]
	v_pk_mul_f32 v[162:163], v[62:63], v[80:81] op_sel_hi:[1,0]
	v_pk_mul_f32 v[168:169], v[64:65], v[80:81] op_sel_hi:[1,0]
	v_pk_mul_f32 v[170:171], v[66:67], v[80:81] op_sel_hi:[1,0]
	s_waitcnt lgkmcnt(0)
; __device__ __forceinline__ void attn_item(const Params& P, const int pass, const int item, const int wvi) {
;     ...
; #pragma unroll
;     for (int d8 = 0; d8 < 8; ++d8)
; #pragma unroll
;       for (int j = 0; j < 4; ++j) oacc[d8][j] *= alpha;
; #pragma unroll
;     for (int kp = 0; kp < 4; ++kp) {
;       const bf16x8 pf = pack8(sc[2 * kp][0], sc[2 * kp][1], sc[2 * kp][2], sc[2 * kp][3],
;                               sc[2 * kp + 1][0], sc[2 * kp + 1][1], sc[2 * kp + 1][2], sc[2 * kp + 1][3]);
; #pragma unroll
;       for (int d8 = 0; d8 < 8; ++d8) {
;         const u16* va = Vs + (kp * 32 + fq * 4 + (fr >> 2)) * LDV + d8 * 16 + (fr & 3) * 4;
;         s16x4 v0 = ldtr(va), v1 = ldtr(va + 16 * LDV);
;         oacc[d8] = __builtin_amdgcn_mfma_f32_16x16x32_bf16(cat8(v0, v1), pf, oacc[d8], 0, 0, 0);
;       }
;     }
	v_add_f32_e32 v82, v140, v82
	v_pk_mul_f32 v[140:141], v[48:49], v[80:81] op_sel_hi:[1,0]
	v_pk_mul_f32 v[48:49], v[76:77], v[80:81] op_sel_hi:[1,0]
	v_add3_u32 v77, s9, v115, v112
	ds_read_b64_tr_b16 v[62:63], v77 offset:39424
	ds_read_b64_tr_b16 v[60:61], v77 offset:34816
	ds_read_b64_tr_b16 v[64:65], v77 offset:34848
	ds_read_b64_tr_b16 v[66:67], v77 offset:39456
	ds_bpermute_b32 v148, v110, v82
	v_pk_mul_f32 v[142:143], v[50:51], v[80:81] op_sel_hi:[1,0]
	v_pk_mul_f32 v[152:153], v[56:57], v[80:81] op_sel_hi:[1,0]
	v_pk_mul_f32 v[154:155], v[58:59], v[80:81] op_sel_hi:[1,0]
	v_pk_mul_f32 v[156:157], v[52:53], v[80:81] op_sel_hi:[1,0]
	v_pk_mul_f32 v[158:159], v[54:55], v[80:81] op_sel_hi:[1,0]
	v_cvt_pk_bf16_f32 v52, v146, v147
	v_cvt_pk_bf16_f32 v53, v150, v164
	v_cvt_pk_bf16_f32 v54, v166, v172
	v_cvt_pk_bf16_f32 v55, v173, v174
	v_pk_mul_f32 v[56:57], v[72:73], v[80:81] op_sel_hi:[1,0]
	v_pk_mul_f32 v[58:59], v[74:75], v[80:81] op_sel_hi:[1,0]
	s_waitcnt lgkmcnt(0)
	v_add_f32_e32 v82, v82, v148
	v_mfma_f32_16x16x32_bf16 v[60:63], v[60:63], v[52:55], v[140:143]
	ds_read_b64_tr_b16 v[72:73], v77 offset:34880
	ds_read_b64_tr_b16 v[74:75], v77 offset:39488
	s_nop 0
	ds_read_b64_tr_b16 v[140:141], v77 offset:34912
	ds_read_b64_tr_b16 v[142:143], v77 offset:39520
	ds_read_b64_tr_b16 v[146:147], v77 offset:34944
	ds_read_b64_tr_b16 v[148:149], v77 offset:39552
	v_mfma_f32_16x16x32_bf16 v[64:67], v[64:67], v[52:55], v[152:155]
	ds_read_b64_tr_b16 v[150:151], v77 offset:34976
	s_nop 1
	ds_read_b64_tr_b16 v[152:153], v77 offset:39584
	v_pk_mul_f32 v[68:69], v[68:69], v[80:81] op_sel_hi:[1,0]
	v_pk_mul_f32 v[70:71], v[70:71], v[80:81] op_sel_hi:[1,0]
	v_pk_mul_f32 v[50:51], v[78:79], v[80:81] op_sel_hi:[1,0]
	s_waitcnt lgkmcnt(6)
	v_mfma_f32_16x16x32_bf16 v[72:75], v[72:75], v[52:55], v[156:159]
	v_add_u32_e32 v76, 0x8800, v77
	v_fmac_f32_e32 v82, v116, v80
	s_waitcnt lgkmcnt(0)
	v_mfma_f32_16x16x32_bf16 v[68:71], v[150:153], v[52:55], v[68:71]
	ds_read_b64_tr_b16 v[150:151], v77 offset:35008
	ds_read_b64_tr_b16 v[152:153], v77 offset:39616
	s_waitcnt lgkmcnt(0)
	v_mfma_f32_16x16x32_bf16 v[56:59], v[150:153], v[52:55], v[56:59]
	ds_read_b64_tr_b16 v[150:151], v77 offset:35040
	ds_read_b64_tr_b16 v[152:153], v77 offset:39648
	v_mfma_f32_16x16x32_bf16 v[140:143], v[140:143], v[52:55], v[160:163]
	v_mfma_f32_16x16x32_bf16 v[146:149], v[146:149], v[52:55], v[168:171]
	s_waitcnt lgkmcnt(0)
	v_mfma_f32_16x16x32_bf16 v[48:51], v[150:153], v[52:55], v[48:51]
	v_cvt_pk_bf16_f32 v52, v132, v133
	v_cvt_pk_bf16_f32 v53, v134, v135
	ds_read_b64_tr_b16 v[132:133], v77 offset:44032
	ds_read_b64_tr_b16 v[134:135], v77 offset:48640
	v_cvt_pk_bf16_f32 v54, v136, v137
	v_cvt_pk_bf16_f32 v55, v138, v139
	s_waitcnt lgkmcnt(0)
	s_nop 0
	v_mfma_f32_16x16x32_bf16 v[60:63], v[132:135], v[52:55], v[60:63]
	ds_read_b64_tr_b16 v[132:133], v77 offset:44064
	ds_read_b64_tr_b16 v[134:135], v77 offset:48672
	s_waitcnt lgkmcnt(0)
	v_mfma_f32_16x16x32_bf16 v[64:67], v[132:135], v[52:55], v[64:67]
	ds_read_b64_tr_b16 v[132:133], v77 offset:44096
	ds_read_b64_tr_b16 v[134:135], v77 offset:48704
	s_waitcnt lgkmcnt(0)
	v_mfma_f32_16x16x32_bf16 v[72:75], v[132:135], v[52:55], v[72:75]
	ds_read_b64_tr_b16 v[132:133], v77 offset:44128
	ds_read_b64_tr_b16 v[134:135], v77 offset:48736
	ds_read_b64_tr_b16 v[136:137], v77 offset:44160
	ds_read_b64_tr_b16 v[138:139], v77 offset:48768
	s_waitcnt lgkmcnt(2)
	v_mfma_f32_16x16x32_bf16 v[132:135], v[132:135], v[52:55], v[140:143]
	s_nop 2
	ds_read_b64_tr_b16 v[140:141], v77 offset:44192
	ds_read_b64_tr_b16 v[142:143], v77 offset:48800
	s_waitcnt lgkmcnt(0)
	v_mfma_f32_16x16x32_bf16 v[68:71], v[140:143], v[52:55], v[68:71]
	ds_read_b64_tr_b16 v[140:141], v77 offset:44224
	ds_read_b64_tr_b16 v[142:143], v77 offset:48832
	s_waitcnt lgkmcnt(0)
; __device__ __forceinline__ void attn_item(const Params& P, const int pass, const int item, const int wvi) {
;     ...
;     for (int kp = 0; kp < 4; ++kp) {
;       const bf16x8 pf = pack8(sc[2 * kp][0], sc[2 * kp][1], sc[2 * kp][2], sc[2 * kp][3],
;                               sc[2 * kp + 1][0], sc[2 * kp + 1][1], sc[2 * kp + 1][2], sc[2 * kp + 1][3]);
; #pragma unroll
;       for (int d8 = 0; d8 < 8; ++d8) {
;         const u16* va = Vs + (kp * 32 + fq * 4 + (fr >> 2)) * LDV + d8 * 16 + (fr & 3) * 4;
;         s16x4 v0 = ldtr(va), v1 = ldtr(va + 16 * LDV);
;         oacc[d8] = __builtin_amdgcn_mfma_f32_16x16x32_bf16(cat8(v0, v1), pf, oacc[d8], 0, 0, 0);
;       }
;     }
	v_mfma_f32_16x16x32_bf16 v[56:59], v[140:143], v[52:55], v[56:59]
	ds_read_b64_tr_b16 v[140:141], v77 offset:44256
	ds_read_b64_tr_b16 v[142:143], v77 offset:48864
	v_mfma_f32_16x16x32_bf16 v[136:139], v[136:139], v[52:55], v[146:149]
	s_waitcnt lgkmcnt(0)
	v_mfma_f32_16x16x32_bf16 v[48:51], v[140:143], v[52:55], v[48:51]
	v_cvt_pk_bf16_f32 v52, v124, v125
	v_cvt_pk_bf16_f32 v53, v126, v127
	ds_read_b64_tr_b16 v[124:125], v77 offset:53248
	ds_read_b64_tr_b16 v[126:127], v77 offset:57856
	v_cvt_pk_bf16_f32 v54, v128, v129
	v_cvt_pk_bf16_f32 v55, v130, v131
	v_cvt_pk_bf16_f32 v140, v83, v117
	v_cvt_pk_bf16_f32 v141, v118, v119
	s_waitcnt lgkmcnt(0)
	v_mfma_f32_16x16x32_bf16 v[60:63], v[124:127], v[52:55], v[60:63]
	ds_read_b64_tr_b16 v[124:125], v77 offset:53280
	ds_read_b64_tr_b16 v[126:127], v77 offset:57888
	v_cvt_pk_bf16_f32 v142, v120, v121
	v_cvt_pk_bf16_f32 v143, v122, v123
	s_waitcnt lgkmcnt(0)
	v_mfma_f32_16x16x32_bf16 v[64:67], v[124:127], v[52:55], v[64:67]
	ds_read_b64_tr_b16 v[124:125], v77 offset:53312
	ds_read_b64_tr_b16 v[126:127], v77 offset:57920
	s_waitcnt lgkmcnt(0)
	v_mfma_f32_16x16x32_bf16 v[72:75], v[124:127], v[52:55], v[72:75]
	ds_read_b64_tr_b16 v[124:125], v77 offset:53344
	ds_read_b64_tr_b16 v[126:127], v77 offset:57952
	ds_read_b64_tr_b16 v[128:129], v77 offset:53376
	ds_read_b64_tr_b16 v[130:131], v77 offset:57984
	s_waitcnt lgkmcnt(2)
	v_mfma_f32_16x16x32_bf16 v[124:127], v[124:127], v[52:55], v[132:135]
	s_nop 2
	ds_read_b64_tr_b16 v[132:133], v77 offset:53408
	ds_read_b64_tr_b16 v[134:135], v77 offset:58016
	s_waitcnt lgkmcnt(0)
	v_mfma_f32_16x16x32_bf16 v[68:71], v[132:135], v[52:55], v[68:71]
	ds_read_b64_tr_b16 v[132:133], v77 offset:53440
	ds_read_b64_tr_b16 v[134:135], v77 offset:58048
	s_waitcnt lgkmcnt(0)
	v_mfma_f32_16x16x32_bf16 v[132:135], v[132:135], v[52:55], v[56:59]
	s_nop 2
	ds_read_b64_tr_b16 v[56:57], v77 offset:53472
	ds_read_b64_tr_b16 v[58:59], v77 offset:58080
	v_mfma_f32_16x16x32_bf16 v[128:131], v[128:131], v[52:55], v[136:139]
	s_waitcnt lgkmcnt(0)
	v_mfma_f32_16x16x32_bf16 v[136:139], v[56:59], v[52:55], v[48:51]
	s_nop 2
	ds_read_b64_tr_b16 v[48:49], v77 offset:62464
	ds_read_b64_tr_b16 v[50:51], v76 offset:32256
	ds_read_b64_tr_b16 v[54:55], v76 offset:32288
	ds_read_b64_tr_b16 v[52:53], v77 offset:62496
	s_waitcnt lgkmcnt(0)
	v_mfma_f32_16x16x32_bf16 v[56:59], v[52:55], v[140:143], v[64:67]
	ds_read_b64_tr_b16 v[52:53], v77 offset:62528
	ds_read_b64_tr_b16 v[54:55], v76 offset:32320
	v_mfma_f32_16x16x32_bf16 v[48:51], v[48:51], v[140:143], v[60:63]
	s_nop 2
	ds_read_b64_tr_b16 v[60:61], v77 offset:62560
	ds_read_b64_tr_b16 v[62:63], v76 offset:32352
	ds_read_b64_tr_b16 v[64:65], v77 offset:62592
	ds_read_b64_tr_b16 v[66:67], v76 offset:32384
	s_waitcnt lgkmcnt(4)
	v_mfma_f32_16x16x32_bf16 v[52:55], v[52:55], v[140:143], v[72:75]
	s_nop 2
	ds_read_b64_tr_b16 v[72:73], v77 offset:62624
	ds_read_b64_tr_b16 v[74:75], v76 offset:32416
	s_waitcnt lgkmcnt(0)
	v_mfma_f32_16x16x32_bf16 v[68:71], v[72:75], v[140:143], v[68:71]
	ds_read_b64_tr_b16 v[72:73], v77 offset:62656
	ds_read_b64_tr_b16 v[74:75], v76 offset:32448
	ds_read_b64_tr_b16 v[118:119], v77 offset:62688
	ds_read_b64_tr_b16 v[120:121], v76 offset:32480
	v_mfma_f32_16x16x32_bf16 v[60:63], v[60:63], v[140:143], v[124:127]
	v_mfma_f32_16x16x32_bf16 v[64:67], v[64:67], v[140:143], v[128:131]
	s_waitcnt lgkmcnt(2)
	v_mfma_f32_16x16x32_bf16 v[72:75], v[72:75], v[140:143], v[132:135]
	s_waitcnt lgkmcnt(0)
	v_mfma_f32_16x16x32_bf16 v[76:79], v[118:121], v[140:143], v[136:139]
	s_cbranch_vccz .LBB0_626
	v_mov_b32_e32 v117, v81
	v_mov_b32_e32 v116, v82
	s_branch .LBB0_560
